# attention: next-tile global loads issued after the first fragment ds_reads (shorter barrier-to-first-MFMA path)
# baseline (speedup 1.0000x reference)
; #define LAS __attribute__((address_space(3)))
; __device__ __forceinline__ void attn_phase(const LArgs& a, LAS unsigned char* lds) {
;     ...
;         for (int j = 0; j < NT; ++j) {
;             const int cur = j & 1;
;             if (j + 1 < NT) ATT_LOAD(j + 1);
;             if (late && j > 0) ATT_PV(vprev, 0);
;             const LAS unsigned char* kb_ = lds + cur * KBUF;
;             f32x16 s[2];
; #pragma unroll
;             for (int kb = 0; kb < 2; ++kb) {
; #pragma unroll
;                 for (int r = 0; r < 16; ++r) s[kb][r] = 0.f;
; #pragma unroll
;                 for (int ks = 0; ks < 4; ++ks) { const bf16x8 kf = *(const LAS bf16x8*)(kb_ + (32 * kb + kappa) * KROW + mp * 128 + ks * 32 + hi * 16);
;                     s[kb] = __builtin_amdgcn_mfma_f32_32x32x16_bf16(kf, qf[ks], s[kb], 0, 0, 0); }
;             }
;             if (!late) ATT_PV_PRE(vcur);
;             float mx = s[0][0];
; #pragma unroll
;             for (int r = 1; r < 16; ++r) mx = fmaxf(mx, s[0][r]);
; #pragma unroll
;             for (int r = 0; r < 16; ++r) mx = fmaxf(mx, s[1][r]);
;             mx = fmaxf(mx, xor32_get(mx, xaddr));
;             const float mnew = fmaxf(mrun, mx);
;             if (__any(mnew > mrun)) {
;                 const float alpha = __builtin_amdgcn_exp2f(mrun - mnew); lrun *= alpha;
; #pragma unroll
;                 for (int d = 0; d < 4; ++d)
; #pragma unroll
;                     for (int r = 0; r < 16; ++r) o[d][r] *= alpha;
;                 mrun = mnew;
;             }
;             float psum = 0.f;
; #pragma unroll
;             for (int kb = 0; kb < 2; ++kb)
; #pragma unroll
;                 for (int r = 0; r < 16; ++r) { const float pv = __builtin_amdgcn_exp2f(s[kb][r] - mrun); s[kb][r] = pv; psum += pv; }
;             lrun += psum;
; #pragma unroll
;             for (int kb = 0; kb < 2; ++kb)
; #pragma unroll
;                 for (int g = 0; g < 2; ++g) {
;                     u32x4 w4; w4.x = pg8::cvt_pk_bf16(s[kb][8 * g + 0], s[kb][8 * g + 1]); w4.y = pg8::cvt_pk_bf16(s[kb][8 * g + 2], s[kb][8 * g + 3]);
;                     w4.z = pg8::cvt_pk_bf16(s[kb][8 * g + 4], s[kb][8 * g + 5]); w4.w = pg8::cvt_pk_bf16(s[kb][8 * g + 6], s[kb][8 * g + 7]);
;                     pw[2 * kb + g] = w4;
;                 }
;             if (!late) ATT_PV(vcur, 1);
;             if (j + 1 < NT) ATT_STORE(cur ^ 1, vnext);
.LBB0_324:
	s_cmpk_lg_i32 s21, 0x103
	s_mov_b32 s22, s0
	s_cselect_b64 s[0:1], -1, 0
	s_and_b32 s23, s21, 1
	s_mul_i32 s16, s23, 0x4400
	s_mul_i32 s24, s22, 0x4800
	v_add_u32_e32 v252, s16, v171
	v_add3_u32 v218, s24, v148, v178
	ds_read_b128 v[96:99], v252
	ds_read_b128 v[100:103], v252 offset:32
	ds_read_b128 v[104:107], v252 offset:64
	ds_read_b128 v[108:111], v252 offset:96
	ds_read_b128 v[182:185], v252 offset:8704
	ds_read_b128 v[186:189], v252 offset:8736
	ds_read_b128 v[224:227], v252 offset:8768
	ds_read_b128 v[244:247], v252 offset:8800
	ds_read_b128 v[174:177], v218 offset:34816
	ds_read_b128 v[248:251], v218 offset:39424
	s_andn2_b64 vcc, exec, s[0:1]
	s_cbranch_vccnz .Lattn_noload
	s_cmp_lt_u32 s21, 3
	s_cselect_b32 s16, s19, s18
	s_ashr_i32 s17, s16, 31
	s_lshl_b64 s[24:25], s[16:17], 11
	v_lshl_add_u64 v[180:181], v[158:159], 0, s[24:25]
	s_or_b32 s24, s16, 32
	s_ashr_i32 s25, s24, 31
	s_lshl_b64 s[24:25], s[24:25], 11
	s_lshl_b64 s[16:17], s[16:17], 1
	global_load_dwordx4 v[128:131], v[180:181], off
	v_lshl_add_u64 v[180:181], v[158:159], 0, s[24:25]
	global_load_dwordx4 v[132:135], v[180:181], off
	v_lshl_add_u64 v[180:181], v[160:161], 0, s[16:17]
	global_load_dwordx4 v[136:139], v[180:181], off
	v_lshl_add_u64 v[180:181], v[162:163], 0, s[16:17]
	global_load_dwordx4 v[140:143], v[180:181], off
.Lattn_noload:
	s_waitcnt lgkmcnt(9)
	v_mfma_f32_32x32x16_bf16 v[228:243], v[96:99], v[112:115], v[202:217]
	ds_read_b128 v[96:99], v218 offset:44032
	s_waitcnt lgkmcnt(9)
	v_mfma_f32_32x32x16_bf16 v[228:243], v[100:103], v[116:119], v[228:243]
	ds_read_b128 v[100:103], v218 offset:48640
	s_waitcnt lgkmcnt(9)
	v_mfma_f32_32x32x16_bf16 v[228:243], v[104:107], v[120:123], v[228:243]
	ds_read_b128 v[104:107], v218 offset:34848
	s_waitcnt lgkmcnt(9)
	v_mfma_f32_32x32x16_bf16 v[228:243], v[108:111], v[124:127], v[228:243]
	ds_read_b128 v[108:111], v218 offset:39456
	s_waitcnt lgkmcnt(9)
	v_mfma_f32_32x32x16_bf16 v[64:79], v[182:185], v[112:115], v[202:217]
	ds_read_b128 v[182:185], v218 offset:44064
	s_waitcnt lgkmcnt(9)
	v_mfma_f32_32x32x16_bf16 v[64:79], v[186:189], v[116:119], v[64:79]
	ds_read_b128 v[186:189], v218 offset:48672
	s_waitcnt lgkmcnt(9)
	v_mfma_f32_32x32x16_bf16 v[64:79], v[224:227], v[120:123], v[64:79]
	ds_read_b128 v[224:227], v218 offset:34880
	s_waitcnt lgkmcnt(9)
	v_mfma_f32_32x32x16_bf16 v[64:79], v[244:247], v[124:127], v[64:79]
	ds_read_b128 v[244:247], v218 offset:39488
	s_waitcnt lgkmcnt(9)
	v_mfma_f32_32x32x16_bf16 v[48:63], v[174:177], v[92:95], v[48:63]
	ds_read_b128 v[174:177], v218 offset:44096
	v_exp_f32_e32 v228, v228
	v_exp_f32_e32 v229, v229
	v_exp_f32_e32 v230, v230
	s_waitcnt lgkmcnt(9)
	v_mfma_f32_32x32x16_bf16 v[32:47], v[248:251], v[92:95], v[32:47]
	ds_read_b128 v[248:251], v218 offset:48704
	v_exp_f32_e32 v231, v231
	v_exp_f32_e32 v232, v232
	v_exp_f32_e32 v233, v233
	s_waitcnt lgkmcnt(9)
	v_mfma_f32_32x32x16_bf16 v[16:31], v[96:99], v[92:95], v[16:31]
	ds_read_b128 v[96:99], v218 offset:34912
	v_exp_f32_e32 v234, v234
	v_exp_f32_e32 v235, v235
	v_exp_f32_e32 v236, v236
	s_waitcnt lgkmcnt(9)
	v_mfma_f32_32x32x16_bf16 v[0:15], v[100:103], v[92:95], v[0:15]
	ds_read_b128 v[100:103], v218 offset:39520
	v_exp_f32_e32 v237, v237
	v_exp_f32_e32 v238, v238
	v_exp_f32_e32 v239, v239
	s_waitcnt lgkmcnt(9)
	v_mfma_f32_32x32x16_bf16 v[48:63], v[104:107], v[88:91], v[48:63]
	ds_read_b128 v[104:107], v218 offset:44128
	v_exp_f32_e32 v240, v240
	v_exp_f32_e32 v241, v241
	v_exp_f32_e32 v242, v242
	s_waitcnt lgkmcnt(9)
	v_mfma_f32_32x32x16_bf16 v[32:47], v[108:111], v[88:91], v[32:47]
	ds_read_b128 v[108:111], v218 offset:48736
	v_exp_f32_e32 v243, v243
	v_exp_f32_e32 v64, v64
	v_add_f32_e32 v190, v228, v229
	v_add_f32_e32 v190, v190, v230
	s_waitcnt lgkmcnt(9)
	v_mfma_f32_32x32x16_bf16 v[16:31], v[182:185], v[88:91], v[16:31]
	v_exp_f32_e32 v65, v65
	v_add_f32_e32 v190, v190, v231
	v_add_f32_e32 v190, v190, v232
	v_exp_f32_e32 v66, v66
	v_add_f32_e32 v190, v190, v233
	s_waitcnt lgkmcnt(8)
	v_mfma_f32_32x32x16_bf16 v[0:15], v[186:189], v[88:91], v[0:15]
	v_add_f32_e32 v190, v190, v234
	v_exp_f32_e32 v67, v67
	v_add_f32_e32 v190, v190, v235
	v_add_f32_e32 v190, v190, v236
	v_exp_f32_e32 v68, v68
	s_andn2_b64 vcc, exec, s[0:1]
	s_cbranch_vccnz .Lattn_nowrite
	s_xor_b32 s0, s23, 1
	s_mulk_i32 s0, 0x4400
	s_mul_i32 s1, s20, 0x4800
	v_add_u32_e32 v219, s0, v168
	s_waitcnt vmcnt(3)
	ds_write_b128 v219, v[128:131]
	s_waitcnt vmcnt(2)
	ds_write_b128 v219, v[132:135] offset:8704
	v_add_u32_e32 v219, s1, v169
	s_waitcnt vmcnt(1)
	ds_write_b128 v219, v[136:139] offset:34816
	s_waitcnt vmcnt(0)
	ds_write_b128 v219, v[140:143] offset:44032
